# attention loop-edge edits: back edge rotated (carried alpha copy before the closing barrier, conditional branch straight to the loop head) and the rescale test done on the scalar all-pass mask instead
# speedup vs baseline: 1.0067x; 1.0002x over previous
; __device__ __forceinline__ void partialSM(f32x16& p0, f32x16& p1, float& m_reg, float& mn, float& alpha) {
;     constexpr float C = SCALE * 1.4426950408889634f;
;     float pmax = p0[0];
; #pragma unroll
;     for (int r = 1; r < 16; ++r) pmax = fmaxf(pmax, p0[r]);
; #pragma unroll
;     for (int r = 0; r < 16; ++r) pmax = fmaxf(pmax, p1[r]);
;     { auto rr = __builtin_amdgcn_permlane32_swap(__float_as_uint(pmax), __float_as_uint(pmax), false, false);
;       pmax = fmaxf(__uint_as_float(rr[0]), __uint_as_float(rr[1])); }
;     if (__builtin_expect(__all(pmax - m_reg <= THR / SCALE), 1)) { mn = m_reg; alpha = 1.f; }
;     else { mn = fmaxf(m_reg, pmax); alpha = __builtin_amdgcn_exp2f((m_reg - mn) * C); m_reg = mn; }
;     const float mnC = -mn * C;
; #pragma unroll
;     for (int r = 0; r < 16; ++r) p0[r] = fmaf(p0[r], C, mnC);
; #pragma unroll
;     for (int r = 0; r < 16; ++r) p1[r] = fmaf(p1[r], C, mnC);
; #pragma unroll
;     for (int r = 0; r < 16; ++r) p0[r] = __builtin_amdgcn_exp2f(p0[r]);
; }
; __device__ __forceinline__ void finishSM(f32x16& p0, f32x16& p1, float alpha, float& l_reg, bf16x8& pa0, bf16x8& pa1, bf16x8& pa2, bf16x8& pa3) {
; #pragma unroll
;     for (int r = 0; r < 16; ++r) p1[r] = __builtin_amdgcn_exp2f(p1[r]);
;     float ps = 0;
; #pragma unroll
;     for (int r = 0; r < 16; ++r) ps += p0[r];
; #pragma unroll
;     for (int r = 0; r < 16; ++r) ps += p1[r];
;     { auto rr = __builtin_amdgcn_permlane32_swap(__float_as_uint(ps), __float_as_uint(ps), false, false);
;       ps = __uint_as_float(rr[0]) + __uint_as_float(rr[1]); }
;     l_reg = l_reg * alpha + ps;
;     ...
;     PK4(p0, 0, pa0); PK4(p0, 8, pa1); PK4(p1, 0, pa2); PK4(p1, 8, pa3);
;     ...
; }
; __device__ __forceinline__ void qkt(f32x16& p0, f32x16& p1, const char* Ks, const bf16x8* qr, int r32, int hi, int comp) {
;     p0 = f32x16{}; p1 = f32x16{};
; #pragma unroll
;     for (int d0 = 0; d0 < 4; ++d0) { const int cb = (comp * 64 + d0 * 16 + hi * 8) * 2;
;         const bf16x8 b0 = *reinterpret_cast<const bf16x8*>(Ks + KSWZ(r32, cb));
;         const bf16x8 b1 = *reinterpret_cast<const bf16x8*>(Ks + KSWZ(32 + r32, cb));
;         p0 = __builtin_amdgcn_mfma_f32_32x32x16_bf16(b0, qr[d0], p0, 0, 0, 0);
;         p1 = __builtin_amdgcn_mfma_f32_32x32x16_bf16(b1, qr[d0], p1, 0, 0, 0); }
; }
.LBB0_262:
	ds_read_b128 v[64:67], v170 offset:49152
	ds_read_b128 v[68:71], v170 offset:57344
	v_add_f32_e32 v177, 0, v240
	v_add_f32_e32 v177, v241, v177
	v_add_f32_e32 v177, v242, v177
	s_waitcnt lgkmcnt(1)
	v_mfma_f32_32x32x16_bf16 v[80:95], v[64:67], v[110:113], 0
	v_add_f32_e32 v177, v243, v177
	v_add_f32_e32 v177, v244, v177
	ds_read_b128 v[178:181], v171 offset:49152
	ds_read_b128 v[220:223], v171 offset:57344
	v_add_f32_e32 v177, v245, v177
	v_add_f32_e32 v177, v246, v177
	v_add_f32_e32 v177, v247, v177
	v_add_f32_e32 v177, v248, v177
	s_waitcnt lgkmcnt(2)
	v_mfma_f32_32x32x16_bf16 v[64:79], v[68:71], v[110:113], 0
	v_add_f32_e32 v177, v249, v177
	v_add_f32_e32 v177, v250, v177
	v_add_f32_e32 v177, v251, v177
	v_exp_f32_e32 v128, v128
	v_add_f32_e32 v177, v206, v177
	v_exp_f32_e32 v129, v129
	v_add_f32_e32 v177, v207, v177
	s_waitcnt lgkmcnt(1)
	v_mfma_f32_32x32x16_bf16 v[80:95], v[178:181], v[106:109], v[80:95]
	v_exp_f32_e32 v126, v126
	v_add_f32_e32 v177, v208, v177
	v_exp_f32_e32 v127, v127
	v_add_f32_e32 v177, v209, v177
	v_exp_f32_e32 v122, v122
	v_add_f32_e32 v177, v128, v177
	v_exp_f32_e32 v123, v123
	s_waitcnt lgkmcnt(0)
	v_mfma_f32_32x32x16_bf16 v[64:79], v[220:223], v[106:109], v[64:79]
	ds_read_b128 v[178:181], v173 offset:49152
	ds_read_b128 v[220:223], v173 offset:57344
	v_add_f32_e32 v177, v129, v177
	v_exp_f32_e32 v118, v118
	v_add_f32_e32 v177, v126, v177
	v_exp_f32_e32 v119, v119
	v_add_f32_e32 v177, v127, v177
	v_exp_f32_e32 v116, v116
	s_waitcnt lgkmcnt(1)
	v_mfma_f32_32x32x16_bf16 v[80:95], v[178:181], v[102:105], v[80:95]
	v_add_f32_e32 v177, v122, v177
	v_exp_f32_e32 v117, v117
	v_add_f32_e32 v177, v123, v177
	v_exp_f32_e32 v124, v124
	v_add_f32_e32 v177, v118, v177
	v_exp_f32_e32 v125, v125
	v_add_f32_e32 v177, v119, v177
	s_waitcnt lgkmcnt(0)
	v_mfma_f32_32x32x16_bf16 v[64:79], v[220:223], v[102:105], v[64:79]
	ds_read_b128 v[178:181], v172 offset:49152
	ds_read_b128 v[220:223], v172 offset:57344
	v_exp_f32_e32 v120, v120
	v_add_f32_e32 v177, v116, v177
	v_exp_f32_e32 v121, v121
	v_add_f32_e32 v177, v117, v177
	v_exp_f32_e32 v114, v114
	v_add_f32_e32 v177, v124, v177
	s_waitcnt lgkmcnt(1)
	v_mfma_f32_32x32x16_bf16 v[80:95], v[178:181], v[98:101], v[80:95]
	v_exp_f32_e32 v115, v115
	v_add_f32_e32 v177, v125, v177
	v_add_f32_e32 v177, v120, v177
	v_add_f32_e32 v177, v121, v177
	v_add_f32_e32 v177, v114, v177
	v_add_f32_e32 v177, v115, v177
	v_mov_b32_e32 v178, v177
	s_waitcnt lgkmcnt(0)
	v_mfma_f32_32x32x16_bf16 v[64:79], v[220:223], v[98:101], v[64:79]
	v_cvt_pk_bf16_f32 v212, v240, v241
	v_cvt_pk_bf16_f32 v213, v242, v243
	v_cvt_pk_bf16_f32 v214, v244, v245
	v_cvt_pk_bf16_f32 v215, v246, v247
	v_cvt_pk_bf16_f32 v180, v248, v249
	v_cvt_pk_bf16_f32 v181, v250, v251
	v_cvt_pk_bf16_f32 v182, v206, v207
	v_permlane32_swap_b32_e32 v177, v178
	v_cvt_pk_bf16_f32 v183, v208, v209
	v_permlane32_swap_b32_e32 v180, v182
	v_cvt_pk_bf16_f32 v184, v128, v129
	v_cvt_pk_bf16_f32 v185, v126, v127
	v_cvt_pk_bf16_f32 v186, v122, v123
	v_cvt_pk_bf16_f32 v187, v118, v119
	v_cvt_pk_bf16_f32 v216, v116, v117
	v_cvt_pk_bf16_f32 v217, v124, v125
	v_cvt_pk_bf16_f32 v218, v120, v121
	v_cvt_pk_bf16_f32 v219, v114, v115
	v_permlane32_swap_b32_e32 v212, v214
	v_permlane32_swap_b32_e32 v213, v215
	v_permlane32_swap_b32_e32 v181, v183
	v_permlane32_swap_b32_e32 v184, v186
	v_permlane32_swap_b32_e32 v185, v187
	v_permlane32_swap_b32_e32 v216, v218
	v_permlane32_swap_b32_e32 v217, v219
	v_add_u32_e32 v122, 0x10000, v176
	global_load_dwordx4 v[240:243], v176, s[58:59]
	global_load_dwordx4 v[244:247], v176, s[28:29]
	global_load_dwordx4 v[206:209], v122, s[58:59]
	s_nop 0
	global_load_dwordx4 v[248:251], v122, s[28:29]
	ds_read_b64_tr_b16 v[220:221], v160 offset:0
	ds_read_b64_tr_b16 v[222:223], v160 offset:0x800
	ds_read_b64_tr_b16 v[224:225], v160 offset:0x1000
	ds_read_b64_tr_b16 v[226:227], v160 offset:0x1800
	ds_read_b64_tr_b16 v[228:229], v160 offset:0x2000
	ds_read_b64_tr_b16 v[230:231], v160 offset:0x2800
	ds_read_b64_tr_b16 v[232:233], v160 offset:0x3000
	ds_read_b64_tr_b16 v[234:235], v160 offset:0x3800
	s_waitcnt lgkmcnt(0)
	v_mfma_f32_32x32x16_bf16 v[48:63], v[212:215], v[220:223], v[48:63]
	ds_read_b64_tr_b16 v[220:221], v160 offset:0x200
	ds_read_b64_tr_b16 v[222:223], v160 offset:0xa00
	v_max_f32_e32 v179, v81, v81
	v_max_f32_e32 v255, v80, v80
	v_max_f32_e32 v179, v255, v179
	v_max3_f32 v179, v179, v82, v83
	v_max3_f32 v179, v179, v84, v85
	v_mfma_f32_32x32x16_bf16 v[48:63], v[180:183], v[224:227], v[48:63]
	ds_read_b64_tr_b16 v[224:225], v160 offset:0x1200
	ds_read_b64_tr_b16 v[226:227], v160 offset:0x1a00
	v_max3_f32 v179, v179, v86, v87
	v_max3_f32 v179, v179, v88, v89
	v_max3_f32 v179, v179, v90, v91
	v_max3_f32 v179, v179, v92, v93
	v_max3_f32 v179, v179, v94, v95
	v_mfma_f32_32x32x16_bf16 v[48:63], v[184:187], v[228:231], v[48:63]
	ds_read_b64_tr_b16 v[228:229], v160 offset:0x2200
	ds_read_b64_tr_b16 v[230:231], v160 offset:0x2a00
	v_max3_f32 v179, v179, v64, v65
	v_max3_f32 v179, v179, v66, v67
	v_max3_f32 v179, v179, v68, v69
	v_max3_f32 v179, v179, v70, v71
	v_max3_f32 v179, v179, v72, v73
	v_mfma_f32_32x32x16_bf16 v[48:63], v[216:219], v[232:235], v[48:63]
	ds_read_b64_tr_b16 v[232:233], v160 offset:0x3200
	ds_read_b64_tr_b16 v[234:235], v160 offset:0x3a00
	v_max3_f32 v179, v179, v74, v75
	v_max3_f32 v179, v179, v76, v77
	v_max3_f32 v179, v179, v78, v79
	v_mov_b32_e32 v255, v179
	s_nop 1
	v_permlane32_swap_b32_e32 v179, v255
	s_waitcnt lgkmcnt(0)
; __device__ __forceinline__ void partialSM(f32x16& p0, f32x16& p1, float& m_reg, float& mn, float& alpha) {
;     ...
;     { auto rr = __builtin_amdgcn_permlane32_swap(__float_as_uint(pmax), __float_as_uint(pmax), false, false);
;       pmax = fmaxf(__uint_as_float(rr[0]), __uint_as_float(rr[1])); }
;     if (__builtin_expect(__all(pmax - m_reg <= THR / SCALE), 1)) { mn = m_reg; alpha = 1.f; }
;     else { mn = fmaxf(m_reg, pmax); alpha = __builtin_amdgcn_exp2f((m_reg - mn) * C); m_reg = mn; }
;     const float mnC = -mn * C;
; #pragma unroll
;     for (int r = 0; r < 16; ++r) p0[r] = fmaf(p0[r], C, mnC);
; #pragma unroll
;     for (int r = 0; r < 16; ++r) p1[r] = fmaf(p1[r], C, mnC);
; #pragma unroll
;     for (int r = 0; r < 16; ++r) p0[r] = __builtin_amdgcn_exp2f(p0[r]);
; }
	v_mfma_f32_32x32x16_bf16 v[32:47], v[212:215], v[220:223], v[32:47]
	ds_read_b64_tr_b16 v[220:221], v160 offset:0x400
	ds_read_b64_tr_b16 v[222:223], v160 offset:0xc00
	v_max_f32_e32 v255, v255, v255
	v_max_f32_e32 v179, v179, v179
	v_max_f32_e32 v179, v179, v255
	v_sub_f32_e32 v255, v179, v175
	v_cmp_ge_f32_e32 vcc, s65, v255
	v_mfma_f32_32x32x16_bf16 v[32:47], v[180:183], v[224:227], v[32:47]
	ds_read_b64_tr_b16 v[224:225], v160 offset:0x1400
	ds_read_b64_tr_b16 v[226:227], v160 offset:0x1c00
	v_max_f32_e32 v255, v175, v175
	v_max_f32_e32 v179, v255, v179
	v_sub_f32_e32 v255, v175, v179
	v_mul_f32_e32 v255, 0x3e38aa3b, v255
	v_exp_f32_e32 v255, v255
	v_mfma_f32_32x32x16_bf16 v[32:47], v[184:187], v[228:231], v[32:47]
	ds_read_b64_tr_b16 v[228:229], v160 offset:0x2400
	ds_read_b64_tr_b16 v[230:231], v160 offset:0x2c00
	s_cmp_eq_u64 vcc, exec
	s_cselect_b64 s[8:9], -1, 0
	v_cndmask_b32_e64 v255, v255, 1.0, s[8:9]
	v_cndmask_b32_e64 v175, v179, v175, s[8:9]
	v_mul_f32_e32 v179, 0xbe38aa3b, v175
	v_mfma_f32_32x32x16_bf16 v[32:47], v[216:219], v[232:235], v[32:47]
	ds_read_b64_tr_b16 v[232:233], v160 offset:0x3400
	ds_read_b64_tr_b16 v[234:235], v160 offset:0x3c00
	v_pk_fma_f32 v[80:81], v[80:81], s[72:73], v[178:179] op_sel:[0,0,1] op_sel_hi:[1,0,1]
	v_pk_fma_f32 v[82:83], v[82:83], s[72:73], v[178:179] op_sel:[0,0,1] op_sel_hi:[1,0,1]
	v_pk_fma_f32 v[84:85], v[84:85], s[72:73], v[178:179] op_sel:[0,0,1] op_sel_hi:[1,0,1]
	v_pk_fma_f32 v[86:87], v[86:87], s[72:73], v[178:179] op_sel:[0,0,1] op_sel_hi:[1,0,1]
	v_pk_fma_f32 v[88:89], v[88:89], s[72:73], v[178:179] op_sel:[0,0,1] op_sel_hi:[1,0,1]
	s_waitcnt lgkmcnt(0)
	v_mfma_f32_32x32x16_bf16 v[16:31], v[212:215], v[220:223], v[16:31]
	ds_read_b64_tr_b16 v[220:221], v160 offset:0x600
	ds_read_b64_tr_b16 v[222:223], v160 offset:0xe00
	v_pk_fma_f32 v[90:91], v[90:91], s[72:73], v[178:179] op_sel:[0,0,1] op_sel_hi:[1,0,1]
	v_pk_fma_f32 v[92:93], v[92:93], s[72:73], v[178:179] op_sel:[0,0,1] op_sel_hi:[1,0,1]
	v_pk_fma_f32 v[94:95], v[94:95], s[72:73], v[178:179] op_sel:[0,0,1] op_sel_hi:[1,0,1]
	v_exp_f32_e32 v127, v80
	v_mfma_f32_32x32x16_bf16 v[16:31], v[180:183], v[224:227], v[16:31]
	ds_read_b64_tr_b16 v[224:225], v160 offset:0x1600
	ds_read_b64_tr_b16 v[226:227], v160 offset:0x1e00
	v_exp_f32_e32 v129, v81
	v_exp_f32_e32 v125, v82
	v_exp_f32_e32 v128, v83
	v_mfma_f32_32x32x16_bf16 v[16:31], v[184:187], v[228:231], v[16:31]
	ds_read_b64_tr_b16 v[228:229], v160 offset:0x2600
	ds_read_b64_tr_b16 v[230:231], v160 offset:0x2e00
	v_exp_f32_e32 v123, v84
	v_exp_f32_e32 v126, v85
	v_exp_f32_e32 v122, v86
	v_mfma_f32_32x32x16_bf16 v[16:31], v[216:219], v[232:235], v[16:31]
	ds_read_b64_tr_b16 v[232:233], v160 offset:0x3600
	ds_read_b64_tr_b16 v[234:235], v160 offset:0x3e00
	v_exp_f32_e32 v124, v87
	v_exp_f32_e32 v119, v88
	v_exp_f32_e32 v121, v89
	s_waitcnt lgkmcnt(0)
	v_mfma_f32_32x32x16_bf16 v[0:15], v[212:215], v[220:223], v[0:15]
	s_barrier
	s_waitcnt vmcnt(0)
	ds_write_b128 v163, v[240:243]
	ds_write_b128 v164, v[206:209]
	ds_write_b128 v161, v[244:247] offset:32768
	ds_write_b128 v162, v[248:251] offset:32768
	v_exp_f32_e32 v117, v90
	v_exp_f32_e32 v120, v91
	v_exp_f32_e32 v115, v92
	v_mfma_f32_32x32x16_bf16 v[0:15], v[180:183], v[224:227], v[0:15]
	v_exp_f32_e32 v118, v93
	v_exp_f32_e32 v114, v94
	v_exp_f32_e32 v116, v95
	v_mfma_f32_32x32x16_bf16 v[0:15], v[184:187], v[228:231], v[0:15]
	v_mfma_f32_32x32x16_bf16 v[0:15], v[216:219], v[232:235], v[0:15]
	v_mov_b32_e32 v180, v255
	s_cmp_lg_u64 s[8:9], 0
	s_cbranch_scc1 .LBB0_266
	s_and_saveexec_b64 s[2:3], s[6:7]
	ds_write_b32 v157, v180 offset:128
	s_or_b64 exec, exec, s[2:3]
	s_waitcnt lgkmcnt(0)
	ds_read_b128 v[240:243], v158 offset:224
	ds_read_b128 v[244:247], v158 offset:192
	ds_read_b128 v[248:251], v158 offset:160
	ds_read_b128 v[206:209], v158 offset:128
	s_waitcnt lgkmcnt(3)
	v_pk_mul_f32 v[62:63], v[62:63], v[242:243]
	s_waitcnt lgkmcnt(2)
	v_pk_mul_f32 v[58:59], v[58:59], v[246:247]
	s_waitcnt lgkmcnt(1)
	v_pk_mul_f32 v[54:55], v[54:55], v[250:251]
	s_waitcnt lgkmcnt(0)
	v_pk_mul_f32 v[50:51], v[50:51], v[208:209]
	v_pk_mul_f32 v[60:61], v[60:61], v[240:241]
	v_pk_mul_f32 v[56:57], v[56:57], v[244:245]
	v_pk_mul_f32 v[52:53], v[52:53], v[248:249]
	v_pk_mul_f32 v[48:49], v[48:49], v[206:207]
	v_pk_mul_f32 v[46:47], v[46:47], v[242:243]
	v_pk_mul_f32 v[42:43], v[42:43], v[246:247]
	v_pk_mul_f32 v[38:39], v[38:39], v[250:251]
	v_pk_mul_f32 v[34:35], v[34:35], v[208:209]
	v_pk_mul_f32 v[44:45], v[44:45], v[240:241]
	v_pk_mul_f32 v[40:41], v[40:41], v[244:245]
	v_pk_mul_f32 v[36:37], v[36:37], v[248:249]
	v_pk_mul_f32 v[32:33], v[32:33], v[206:207]
	v_pk_mul_f32 v[30:31], v[30:31], v[242:243]
	v_pk_mul_f32 v[26:27], v[26:27], v[246:247]
	v_pk_mul_f32 v[22:23], v[22:23], v[250:251]
	v_pk_mul_f32 v[18:19], v[18:19], v[208:209]
	v_pk_mul_f32 v[28:29], v[28:29], v[240:241]
	v_pk_mul_f32 v[24:25], v[24:25], v[244:245]
	v_pk_mul_f32 v[20:21], v[20:21], v[248:249]
	v_pk_mul_f32 v[16:17], v[16:17], v[206:207]
	v_pk_mul_f32 v[14:15], v[14:15], v[242:243]
	v_pk_mul_f32 v[10:11], v[10:11], v[246:247]
	v_pk_mul_f32 v[6:7], v[6:7], v[250:251]
	v_pk_mul_f32 v[2:3], v[2:3], v[208:209]
	v_pk_mul_f32 v[12:13], v[12:13], v[240:241]
	v_pk_mul_f32 v[8:9], v[8:9], v[244:245]
	v_pk_mul_f32 v[4:5], v[4:5], v[248:249]
	v_pk_mul_f32 v[0:1], v[0:1], v[206:207]
; __device__ __forceinline__ void partialSM(f32x16& p0, f32x16& p1, float& m_reg, float& mn, float& alpha) {
;     constexpr float C = SCALE * 1.4426950408889634f;
;     float pmax = p0[0];
; #pragma unroll
;     for (int r = 1; r < 16; ++r) pmax = fmaxf(pmax, p0[r]);
; #pragma unroll
;     for (int r = 0; r < 16; ++r) pmax = fmaxf(pmax, p1[r]);
;     { auto rr = __builtin_amdgcn_permlane32_swap(__float_as_uint(pmax), __float_as_uint(pmax), false, false);
;       pmax = fmaxf(__uint_as_float(rr[0]), __uint_as_float(rr[1])); }
;     if (__builtin_expect(__all(pmax - m_reg <= THR / SCALE), 1)) { mn = m_reg; alpha = 1.f; }
;     else { mn = fmaxf(m_reg, pmax); alpha = __builtin_amdgcn_exp2f((m_reg - mn) * C); m_reg = mn; }
;     const float mnC = -mn * C;
; #pragma unroll
;     for (int r = 0; r < 16; ++r) p0[r] = fmaf(p0[r], C, mnC);
; #pragma unroll
;     for (int r = 0; r < 16; ++r) p1[r] = fmaf(p1[r], C, mnC);
; #pragma unroll
;     for (int r = 0; r < 16; ++r) p0[r] = __builtin_amdgcn_exp2f(p0[r]);
; }
; __device__ __forceinline__ void finishSM(f32x16& p0, f32x16& p1, float alpha, float& l_reg, bf16x8& pa0, bf16x8& pa1, bf16x8& pa2, bf16x8& pa3) {
; #pragma unroll
;     for (int r = 0; r < 16; ++r) p1[r] = __builtin_amdgcn_exp2f(p1[r]);
;     float ps = 0;
; #pragma unroll
;     for (int r = 0; r < 16; ++r) ps += p0[r];
; #pragma unroll
;     for (int r = 0; r < 16; ++r) ps += p1[r];
;     { auto rr = __builtin_amdgcn_permlane32_swap(__float_as_uint(ps), __float_as_uint(ps), false, false);
;       ps = __uint_as_float(rr[0]) + __uint_as_float(rr[1]); }
;     l_reg = l_reg * alpha + ps;
;     ...
;     PK4(p0, 0, pa0); PK4(p0, 8, pa1); PK4(p1, 0, pa2); PK4(p1, 8, pa3);
;     ...
; }
; __device__ __forceinline__ void qkt(f32x16& p0, f32x16& p1, const char* Ks, const bf16x8* qr, int r32, int hi, int comp) {
;     p0 = f32x16{}; p1 = f32x16{};
; #pragma unroll
;     for (int d0 = 0; d0 < 4; ++d0) { const int cb = (comp * 64 + d0 * 16 + hi * 8) * 2;
;         const bf16x8 b0 = *reinterpret_cast<const bf16x8*>(Ks + KSWZ(r32, cb));
;         const bf16x8 b1 = *reinterpret_cast<const bf16x8*>(Ks + KSWZ(32 + r32, cb));
;         p0 = __builtin_amdgcn_mfma_f32_32x32x16_bf16(b0, qr[d0], p0, 0, 0, 0);
;         p1 = __builtin_amdgcn_mfma_f32_32x32x16_bf16(b1, qr[d0], p1, 0, 0, 0); }
; }
.LBB0_266:
	v_fmamk_f32 v189, v64, 0x3e38aa3b, v179
	v_fmamk_f32 v211, v65, 0x3e38aa3b, v179
	v_fmamk_f32 v212, v66, 0x3e38aa3b, v179
	v_fmamk_f32 v213, v67, 0x3e38aa3b, v179
	v_fmamk_f32 v214, v68, 0x3e38aa3b, v179
	v_fmamk_f32 v182, v69, 0x3e38aa3b, v179
	v_fmamk_f32 v183, v70, 0x3e38aa3b, v179
	v_fmamk_f32 v184, v71, 0x3e38aa3b, v179
	v_fmamk_f32 v185, v72, 0x3e38aa3b, v179
	v_fmamk_f32 v186, v73, 0x3e38aa3b, v179
	v_fmamk_f32 v187, v74, 0x3e38aa3b, v179
	v_fmamk_f32 v188, v75, 0x3e38aa3b, v179
	v_fmamk_f32 v181, v76, 0x3e38aa3b, v179
	v_fmamk_f32 v215, v77, 0x3e38aa3b, v179
	v_fmamk_f32 v216, v78, 0x3e38aa3b, v179
	v_fmac_f32_e32 v179, 0x3e38aa3b, v79
	s_waitcnt lgkmcnt(0)
	s_barrier
	ds_read_b128 v[64:67], v170 offset:32768
	ds_read_b128 v[68:71], v170 offset:40960
	v_exp_f32_e32 v203, v181
	v_add_f32_e32 v181, 0, v127
	v_add_f32_e32 v181, v129, v181
	s_waitcnt lgkmcnt(1)
	v_mfma_f32_32x32x16_bf16 v[80:95], v[64:67], v[110:113], 0
	v_add_f32_e32 v181, v125, v181
	v_add_f32_e32 v181, v128, v181
	v_add_f32_e32 v181, v123, v181
	ds_read_b128 v[218:221], v171 offset:32768
	ds_read_b128 v[222:225], v171 offset:40960
	v_add_f32_e32 v181, v126, v181
	v_add_f32_e32 v181, v122, v181
	v_add_f32_e32 v181, v124, v181
	s_waitcnt lgkmcnt(2)
	v_mfma_f32_32x32x16_bf16 v[64:79], v[68:71], v[110:113], 0
	v_add_f32_e32 v181, v119, v181
	v_add_f32_e32 v181, v121, v181
	v_add_f32_e32 v181, v117, v181
	v_add_f32_e32 v181, v120, v181
	v_exp_f32_e32 v189, v189
	v_add_f32_e32 v181, v115, v181
	v_exp_f32_e32 v190, v211
	s_waitcnt lgkmcnt(1)
	v_mfma_f32_32x32x16_bf16 v[80:95], v[218:221], v[106:109], v[80:95]
	v_add_f32_e32 v181, v118, v181
	v_exp_f32_e32 v191, v212
	v_add_f32_e32 v181, v114, v181
	v_exp_f32_e32 v192, v213
	v_add_f32_e32 v181, v116, v181
	v_exp_f32_e32 v193, v214
	v_add_f32_e32 v181, v189, v181
	s_waitcnt lgkmcnt(0)
	v_mfma_f32_32x32x16_bf16 v[64:79], v[222:225], v[106:109], v[64:79]
	ds_read_b128 v[218:221], v173 offset:32768
	ds_read_b128 v[222:225], v173 offset:40960
	v_exp_f32_e32 v194, v182
	v_add_f32_e32 v181, v190, v181
	v_exp_f32_e32 v183, v183
	v_add_f32_e32 v181, v191, v181
	v_exp_f32_e32 v195, v184
	v_add_f32_e32 v181, v192, v181
	s_waitcnt lgkmcnt(1)
	v_mfma_f32_32x32x16_bf16 v[80:95], v[218:221], v[102:105], v[80:95]
	v_exp_f32_e32 v200, v185
	v_add_f32_e32 v181, v193, v181
	v_exp_f32_e32 v201, v186
	v_add_f32_e32 v181, v194, v181
	v_exp_f32_e32 v202, v187
	v_add_f32_e32 v181, v183, v181
	v_exp_f32_e32 v188, v188
	s_waitcnt lgkmcnt(0)
	v_mfma_f32_32x32x16_bf16 v[64:79], v[222:225], v[102:105], v[64:79]
	ds_read_b128 v[218:221], v172 offset:32768
	ds_read_b128 v[222:225], v172 offset:40960
	v_add_f32_e32 v181, v195, v181
	v_add_f32_e32 v181, v200, v181
	v_exp_f32_e32 v204, v215
	v_add_f32_e32 v181, v201, v181
	v_exp_f32_e32 v205, v216
	v_add_f32_e32 v181, v202, v181
	s_waitcnt lgkmcnt(1)
	v_mfma_f32_32x32x16_bf16 v[80:95], v[218:221], v[98:101], v[80:95]
	v_exp_f32_e32 v179, v179
	v_add_f32_e32 v181, v188, v181
	v_add_f32_e32 v181, v203, v181
	v_add_f32_e32 v181, v204, v181
	v_add_f32_e32 v181, v205, v181
	v_add_f32_e32 v181, v179, v181
	v_mov_b32_e32 v182, v181
	s_waitcnt lgkmcnt(0)
	v_mfma_f32_32x32x16_bf16 v[64:79], v[222:225], v[98:101], v[64:79]
	v_permlane32_swap_b32_e32 v181, v182
	v_cvt_pk_bf16_f32 v184, v127, v129
	v_cvt_pk_bf16_f32 v185, v125, v128
	v_cvt_pk_bf16_f32 v186, v123, v126
	v_cvt_pk_bf16_f32 v187, v122, v124
	v_cvt_pk_bf16_f32 v212, v119, v121
	v_cvt_pk_bf16_f32 v213, v117, v120
	v_cvt_pk_bf16_f32 v214, v115, v118
	v_cvt_pk_bf16_f32 v215, v114, v116
	v_cvt_pk_bf16_f32 v216, v189, v190
	v_cvt_pk_bf16_f32 v217, v191, v192
	v_cvt_pk_bf16_f32 v218, v193, v194
	v_cvt_pk_bf16_f32 v219, v183, v195
	v_cvt_pk_bf16_f32 v220, v200, v201
	v_cvt_pk_bf16_f32 v221, v202, v188
	v_cvt_pk_bf16_f32 v222, v203, v204
	v_cvt_pk_bf16_f32 v223, v205, v179
	s_nop 0
	v_permlane32_swap_b32_e32 v184, v186
	v_permlane32_swap_b32_e32 v185, v187
	v_permlane32_swap_b32_e32 v212, v214
	v_permlane32_swap_b32_e32 v213, v215
	v_permlane32_swap_b32_e32 v216, v218
	v_permlane32_swap_b32_e32 v217, v219
	v_permlane32_swap_b32_e32 v220, v222
	v_permlane32_swap_b32_e32 v221, v223
	v_add_u32_e32 v118, 0x20000, v176
	v_add_u32_e32 v122, 0x30000, v176
	global_load_dwordx4 v[114:117], v118, s[58:59]
	s_nop 0
	global_load_dwordx4 v[118:121], v118, s[28:29]
	s_nop 0
	global_load_dwordx4 v[126:129], v122, s[58:59]
	s_nop 0
	global_load_dwordx4 v[122:125], v122, s[28:29]
	ds_read_b64_tr_b16 v[224:225], v159 offset:0
	ds_read_b64_tr_b16 v[226:227], v159 offset:0x800
	ds_read_b64_tr_b16 v[228:229], v159 offset:0x1000
	ds_read_b64_tr_b16 v[230:231], v159 offset:0x1800
	ds_read_b64_tr_b16 v[232:233], v159 offset:0x2000
	ds_read_b64_tr_b16 v[234:235], v159 offset:0x2800
	ds_read_b64_tr_b16 v[236:237], v159 offset:0x3000
	ds_read_b64_tr_b16 v[238:239], v159 offset:0x3800
	s_waitcnt lgkmcnt(0)
	v_mfma_f32_32x32x16_bf16 v[48:63], v[184:187], v[224:227], v[48:63]
	ds_read_b64_tr_b16 v[224:225], v159 offset:0x200
	ds_read_b64_tr_b16 v[226:227], v159 offset:0xa00
	v_max_f32_e32 v255, v81, v81
	v_max_f32_e32 v210, v80, v80
	v_max_f32_e32 v255, v210, v255
	v_max3_f32 v255, v255, v82, v83
	v_max3_f32 v255, v255, v84, v85
	v_mfma_f32_32x32x16_bf16 v[48:63], v[212:215], v[228:231], v[48:63]
	ds_read_b64_tr_b16 v[228:229], v159 offset:0x1200
	ds_read_b64_tr_b16 v[230:231], v159 offset:0x1a00
	v_max3_f32 v255, v255, v86, v87
	v_max3_f32 v255, v255, v88, v89
	v_max3_f32 v255, v255, v90, v91
	v_max3_f32 v255, v255, v92, v93
	v_max3_f32 v255, v255, v94, v95
	v_mfma_f32_32x32x16_bf16 v[48:63], v[216:219], v[232:235], v[48:63]
	ds_read_b64_tr_b16 v[232:233], v159 offset:0x2200
	ds_read_b64_tr_b16 v[234:235], v159 offset:0x2a00
	v_max3_f32 v255, v255, v64, v65
	v_max3_f32 v255, v255, v66, v67
	v_max3_f32 v255, v255, v68, v69
	v_max3_f32 v255, v255, v70, v71
	v_max3_f32 v255, v255, v72, v73
	v_mfma_f32_32x32x16_bf16 v[48:63], v[220:223], v[236:239], v[48:63]
	ds_read_b64_tr_b16 v[236:237], v159 offset:0x3200
	ds_read_b64_tr_b16 v[238:239], v159 offset:0x3a00
	v_max3_f32 v255, v255, v74, v75
	v_max3_f32 v255, v255, v76, v77
	v_max3_f32 v255, v255, v78, v79
	v_mov_b32_e32 v210, v255
	s_nop 1
	v_permlane32_swap_b32_e32 v255, v210
	s_waitcnt lgkmcnt(0)
; __device__ __forceinline__ void partialSM(f32x16& p0, f32x16& p1, float& m_reg, float& mn, float& alpha) {
;     ...
;     { auto rr = __builtin_amdgcn_permlane32_swap(__float_as_uint(pmax), __float_as_uint(pmax), false, false);
;       pmax = fmaxf(__uint_as_float(rr[0]), __uint_as_float(rr[1])); }
;     if (__builtin_expect(__all(pmax - m_reg <= THR / SCALE), 1)) { mn = m_reg; alpha = 1.f; }
;     else { mn = fmaxf(m_reg, pmax); alpha = __builtin_amdgcn_exp2f((m_reg - mn) * C); m_reg = mn; }
;     const float mnC = -mn * C;
; #pragma unroll
;     for (int r = 0; r < 16; ++r) p0[r] = fmaf(p0[r], C, mnC);
; #pragma unroll
;     for (int r = 0; r < 16; ++r) p1[r] = fmaf(p1[r], C, mnC);
; #pragma unroll
;     for (int r = 0; r < 16; ++r) p0[r] = __builtin_amdgcn_exp2f(p0[r]);
; }
; __device__ __forceinline__ void finishSM(f32x16& p0, f32x16& p1, float alpha, float& l_reg, bf16x8& pa0, bf16x8& pa1, bf16x8& pa2, bf16x8& pa3) {
; #pragma unroll
;     for (int r = 0; r < 16; ++r) p1[r] = __builtin_amdgcn_exp2f(p1[r]);
;     float ps = 0;
; #pragma unroll
;     for (int r = 0; r < 16; ++r) ps += p0[r];
; #pragma unroll
;     for (int r = 0; r < 16; ++r) ps += p1[r];
;     { auto rr = __builtin_amdgcn_permlane32_swap(__float_as_uint(ps), __float_as_uint(ps), false, false);
;       ps = __uint_as_float(rr[0]) + __uint_as_float(rr[1]); }
;     l_reg = l_reg * alpha + ps;
; __device__ __forceinline__ void attn_unit(const bf16_t* Qb, const bf16_t* Kh, const bf16_t* Vh, bf16_t* Ob, float* scr, int seq, float lam, float onemli, const float* subg, char* lds) {
;     ...
;         f32x16 pA0, pA1, pB0, pB1; float mnA, mnB, alA, alB; bf16x8 pa0, pa1, pa2, pa3;
;         constexpr int SE = 0, SO = 0;
;         __syncthreads();
;         SLOAD(SE, 0); asm volatile("s_waitcnt vmcnt(0)" ::: "memory"); SWRITE(0, SE); __syncthreads();
;         qkt(pA0, pA1, K_lds, qr, r32, hi, comp); partialSM(pA0, pA1, m_reg, mnA, alA);
;         SLOAD(SO, KVBLK);
;         SWAIT(); SWRITE(1, SO); __syncthreads();
;         for (int j = 1; j + 1 < NT; j += 2) {
;             SBAR(); qkt(pB0, pB1, K_lds + SHM_K, qr, r32, hi, comp);
;             finishSM(pA0, pA1, alA, l_reg, pa0, pa1, pa2, pa3); SBAR();
;             SLOAD(SO, (j + 1) * KVBLK); SBAR();
;             pv_d0(o, vb0, pa0, pa1, pa2, pa3); partialSM(pB0, pB1, m_reg, mnB, alB);
;             __syncthreads(); SWAIT(); SWRITE(0, SE);
	v_mfma_f32_32x32x16_bf16 v[32:47], v[184:187], v[224:227], v[32:47]
	ds_read_b64_tr_b16 v[224:225], v159 offset:0x400
	ds_read_b64_tr_b16 v[226:227], v159 offset:0xc00
	v_max_f32_e32 v210, v210, v210
	v_max_f32_e32 v255, v255, v255
	v_max_f32_e32 v255, v255, v210
	v_sub_f32_e32 v210, v255, v175
	v_cmp_ge_f32_e32 vcc, s65, v210
	v_mfma_f32_32x32x16_bf16 v[32:47], v[212:215], v[228:231], v[32:47]
	ds_read_b64_tr_b16 v[228:229], v159 offset:0x1400
	ds_read_b64_tr_b16 v[230:231], v159 offset:0x1c00
	v_max_f32_e32 v210, v175, v175
	v_max_f32_e32 v210, v210, v255
	v_sub_f32_e32 v255, v175, v210
	v_mul_f32_e32 v255, 0x3e38aa3b, v255
	v_exp_f32_e32 v255, v255
	v_mfma_f32_32x32x16_bf16 v[32:47], v[216:219], v[232:235], v[32:47]
	ds_read_b64_tr_b16 v[232:233], v159 offset:0x2400
	ds_read_b64_tr_b16 v[234:235], v159 offset:0x2c00
	s_cmp_eq_u64 vcc, exec
	s_cselect_b64 s[8:9], -1, 0
	v_cndmask_b32_e64 v255, v255, 1.0, s[8:9]
	v_cndmask_b32_e64 v175, v210, v175, s[8:9]
	v_mul_f32_e32 v210, 0xbe38aa3b, v175
	v_mfma_f32_32x32x16_bf16 v[32:47], v[220:223], v[236:239], v[32:47]
	ds_read_b64_tr_b16 v[236:237], v159 offset:0x3400
	ds_read_b64_tr_b16 v[238:239], v159 offset:0x3c00
	v_pk_fma_f32 v[80:81], v[80:81], s[72:73], v[210:211] op_sel_hi:[1,0,0]
	v_pk_fma_f32 v[82:83], v[82:83], s[72:73], v[210:211] op_sel_hi:[1,0,0]
	v_pk_fma_f32 v[84:85], v[84:85], s[72:73], v[210:211] op_sel_hi:[1,0,0]
	v_pk_fma_f32 v[86:87], v[86:87], s[72:73], v[210:211] op_sel_hi:[1,0,0]
	v_pk_fma_f32 v[88:89], v[88:89], s[72:73], v[210:211] op_sel_hi:[1,0,0]
	s_waitcnt lgkmcnt(0)
	v_mfma_f32_32x32x16_bf16 v[16:31], v[184:187], v[224:227], v[16:31]
	ds_read_b64_tr_b16 v[224:225], v159 offset:0x600
	ds_read_b64_tr_b16 v[226:227], v159 offset:0xe00
	v_pk_fma_f32 v[90:91], v[90:91], s[72:73], v[210:211] op_sel_hi:[1,0,0]
	v_pk_fma_f32 v[92:93], v[92:93], s[72:73], v[210:211] op_sel_hi:[1,0,0]
	v_pk_fma_f32 v[94:95], v[94:95], s[72:73], v[210:211] op_sel_hi:[1,0,0]
	v_exp_f32_e32 v240, v80
	v_mfma_f32_32x32x16_bf16 v[16:31], v[212:215], v[228:231], v[16:31]
	ds_read_b64_tr_b16 v[228:229], v159 offset:0x1600
	ds_read_b64_tr_b16 v[230:231], v159 offset:0x1e00
	v_exp_f32_e32 v241, v81
	v_exp_f32_e32 v242, v82
	v_exp_f32_e32 v243, v83
	v_mfma_f32_32x32x16_bf16 v[16:31], v[216:219], v[232:235], v[16:31]
	ds_read_b64_tr_b16 v[232:233], v159 offset:0x2600
	ds_read_b64_tr_b16 v[234:235], v159 offset:0x2e00
	v_exp_f32_e32 v244, v84
	v_exp_f32_e32 v245, v85
	v_exp_f32_e32 v246, v86
	v_mfma_f32_32x32x16_bf16 v[16:31], v[220:223], v[236:239], v[16:31]
	ds_read_b64_tr_b16 v[236:237], v159 offset:0x3600
	ds_read_b64_tr_b16 v[238:239], v159 offset:0x3e00
	v_exp_f32_e32 v247, v87
	v_exp_f32_e32 v248, v88
	v_exp_f32_e32 v249, v89
	s_waitcnt lgkmcnt(0)
	v_mfma_f32_32x32x16_bf16 v[0:15], v[184:187], v[224:227], v[0:15]
	s_barrier
	s_waitcnt vmcnt(0)
	ds_write_b128 v163, v[114:117] offset:16384
	ds_write_b128 v164, v[126:129] offset:16384
	ds_write_b128 v161, v[118:121] offset:49152
	ds_write_b128 v162, v[122:125] offset:49152
	v_exp_f32_e32 v250, v90
	v_exp_f32_e32 v251, v91
	v_exp_f32_e32 v206, v92
	v_mfma_f32_32x32x16_bf16 v[0:15], v[212:215], v[228:231], v[0:15]
	v_exp_f32_e32 v207, v93
	v_exp_f32_e32 v208, v94
	v_exp_f32_e32 v209, v95
	v_mfma_f32_32x32x16_bf16 v[0:15], v[216:219], v[232:235], v[0:15]
	v_mfma_f32_32x32x16_bf16 v[0:15], v[220:223], v[236:239], v[0:15]
	v_mov_b32_e32 v179, v255
	s_cmp_lg_u64 s[8:9], 0
	s_cbranch_scc1 .LBB0_270
	s_and_saveexec_b64 s[2:3], s[6:7]
	ds_write_b32 v157, v179 offset:128
	s_or_b64 exec, exec, s[2:3]
	s_waitcnt lgkmcnt(0)
	ds_read_b128 v[114:117], v158 offset:224
	ds_read_b128 v[118:121], v158 offset:192
	ds_read_b128 v[122:125], v158 offset:160
	ds_read_b128 v[126:129], v158 offset:128
	s_waitcnt lgkmcnt(3)
	v_pk_mul_f32 v[62:63], v[62:63], v[116:117]
	s_waitcnt lgkmcnt(2)
	v_pk_mul_f32 v[58:59], v[58:59], v[120:121]
	s_waitcnt lgkmcnt(1)
	v_pk_mul_f32 v[54:55], v[54:55], v[124:125]
	s_waitcnt lgkmcnt(0)
	v_pk_mul_f32 v[50:51], v[50:51], v[128:129]
	v_pk_mul_f32 v[60:61], v[60:61], v[114:115]
	v_pk_mul_f32 v[56:57], v[56:57], v[118:119]
	v_pk_mul_f32 v[52:53], v[52:53], v[122:123]
	v_pk_mul_f32 v[48:49], v[48:49], v[126:127]
	v_pk_mul_f32 v[46:47], v[46:47], v[116:117]
	v_pk_mul_f32 v[42:43], v[42:43], v[120:121]
	v_pk_mul_f32 v[38:39], v[38:39], v[124:125]
	v_pk_mul_f32 v[34:35], v[34:35], v[128:129]
	v_pk_mul_f32 v[44:45], v[44:45], v[114:115]
	v_pk_mul_f32 v[40:41], v[40:41], v[118:119]
	v_pk_mul_f32 v[36:37], v[36:37], v[122:123]
	v_pk_mul_f32 v[32:33], v[32:33], v[126:127]
	v_pk_mul_f32 v[30:31], v[30:31], v[116:117]
	v_pk_mul_f32 v[26:27], v[26:27], v[120:121]
	v_pk_mul_f32 v[22:23], v[22:23], v[124:125]
	v_pk_mul_f32 v[18:19], v[18:19], v[128:129]
	v_pk_mul_f32 v[28:29], v[28:29], v[114:115]
	v_pk_mul_f32 v[24:25], v[24:25], v[118:119]
	v_pk_mul_f32 v[20:21], v[20:21], v[122:123]
	v_pk_mul_f32 v[16:17], v[16:17], v[126:127]
	v_pk_mul_f32 v[14:15], v[14:15], v[116:117]
	v_pk_mul_f32 v[10:11], v[10:11], v[120:121]
	v_pk_mul_f32 v[6:7], v[6:7], v[124:125]
	v_pk_mul_f32 v[2:3], v[2:3], v[128:129]
	v_pk_mul_f32 v[12:13], v[12:13], v[114:115]
	v_pk_mul_f32 v[8:9], v[8:9], v[118:119]
	v_pk_mul_f32 v[4:5], v[4:5], v[122:123]
	v_pk_mul_f32 v[0:1], v[0:1], v[126:127]
.LBB0_270:
	v_mov_b32_e32 v114, v210
	v_pk_fma_f32 v[128:129], v[64:65], s[72:73], v[114:115] op_sel_hi:[1,0,0]
	v_add_f32_e32 v64, v177, v178
	v_fmac_f32_e32 v64, v174, v169
	v_add_f32_e32 v169, v181, v182
	s_add_i32 s76, s76, 2
	v_pk_fma_f32 v[126:127], v[66:67], s[72:73], v[114:115] op_sel_hi:[1,0,0]
	v_pk_fma_f32 v[122:123], v[68:69], s[72:73], v[114:115] op_sel_hi:[1,0,0]
	v_pk_fma_f32 v[118:119], v[70:71], s[72:73], v[114:115] op_sel_hi:[1,0,0]
	v_pk_fma_f32 v[116:117], v[72:73], s[72:73], v[114:115] op_sel_hi:[1,0,0]
	v_pk_fma_f32 v[124:125], v[74:75], s[72:73], v[114:115] op_sel_hi:[1,0,0]
	v_pk_fma_f32 v[120:121], v[76:77], s[72:73], v[114:115] op_sel_hi:[1,0,0]
	v_pk_fma_f32 v[114:115], v[78:79], s[72:73], v[114:115] op_sel_hi:[1,0,0]
	v_fmac_f32_e32 v169, v64, v180
	s_cmp_ge_u32 s76, s67
	v_add_u32_e32 v176, 0x40000, v176
	v_mov_b32_e32 v174, v179
	s_waitcnt lgkmcnt(0)
	s_barrier
	s_cbranch_scc0 .LBB0_262

; __device__ __forceinline__ void partialSM(f32x16& p0, f32x16& p1, float& m_reg, float& mn, float& alpha) {
;     constexpr float C = SCALE * 1.4426950408889634f;
;     float pmax = p0[0];
; #pragma unroll
;     for (int r = 1; r < 16; ++r) pmax = fmaxf(pmax, p0[r]);
; #pragma unroll
;     for (int r = 0; r < 16; ++r) pmax = fmaxf(pmax, p1[r]);
;     { auto rr = __builtin_amdgcn_permlane32_swap(__float_as_uint(pmax), __float_as_uint(pmax), false, false);
;       pmax = fmaxf(__uint_as_float(rr[0]), __uint_as_float(rr[1])); }
;     if (__builtin_expect(__all(pmax - m_reg <= THR / SCALE), 1)) { mn = m_reg; alpha = 1.f; }
;     else { mn = fmaxf(m_reg, pmax); alpha = __builtin_amdgcn_exp2f((m_reg - mn) * C); m_reg = mn; }
;     const float mnC = -mn * C;
; #pragma unroll
;     for (int r = 0; r < 16; ++r) p0[r] = fmaf(p0[r], C, mnC);
; #pragma unroll
;     for (int r = 0; r < 16; ++r) p1[r] = fmaf(p1[r], C, mnC);
; #pragma unroll
;     for (int r = 0; r < 16; ++r) p0[r] = __builtin_amdgcn_exp2f(p0[r]);
; }
; __device__ __forceinline__ void finishSM(f32x16& p0, f32x16& p1, float alpha, float& l_reg, bf16x8& pa0, bf16x8& pa1, bf16x8& pa2, bf16x8& pa3) {
; #pragma unroll
;     for (int r = 0; r < 16; ++r) p1[r] = __builtin_amdgcn_exp2f(p1[r]);
;     float ps = 0;
; #pragma unroll
;     for (int r = 0; r < 16; ++r) ps += p0[r];
; #pragma unroll
;     for (int r = 0; r < 16; ++r) ps += p1[r];
;     { auto rr = __builtin_amdgcn_permlane32_swap(__float_as_uint(ps), __float_as_uint(ps), false, false);
;       ps = __uint_as_float(rr[0]) + __uint_as_float(rr[1]); }
;     l_reg = l_reg * alpha + ps;
;     ...
;     PK4(p0, 0, pa0); PK4(p0, 8, pa1); PK4(p1, 0, pa2); PK4(p1, 8, pa3);
;     ...
; }
; __device__ __forceinline__ void qkt(f32x16& p0, f32x16& p1, const char* Ks, const bf16x8* qr, int r32, int hi, int comp) {
;     p0 = f32x16{}; p1 = f32x16{};
; #pragma unroll
;     for (int d0 = 0; d0 < 4; ++d0) { const int cb = (comp * 64 + d0 * 16 + hi * 8) * 2;
;         const bf16x8 b0 = *reinterpret_cast<const bf16x8*>(Ks + KSWZ(r32, cb));
;         const bf16x8 b1 = *reinterpret_cast<const bf16x8*>(Ks + KSWZ(32 + r32, cb));
;         p0 = __builtin_amdgcn_mfma_f32_32x32x16_bf16(b0, qr[d0], p0, 0, 0, 0);
;         p1 = __builtin_amdgcn_mfma_f32_32x32x16_bf16(b1, qr[d0], p1, 0, 0, 0); }
; }
.LBB0_280:
	ds_read_b128 v[64:67], v140 offset:49152
	ds_read_b128 v[68:71], v140 offset:57344
	v_add_f32_e32 v135, 0, v240
	v_add_f32_e32 v135, v241, v135
	v_add_f32_e32 v135, v242, v135
	s_waitcnt lgkmcnt(1)
	v_mfma_f32_32x32x16_bf16 v[80:95], v[64:67], v[110:113], 0
	v_add_f32_e32 v135, v243, v135
	v_add_f32_e32 v135, v244, v135
	ds_read_b128 v[136:139], v143 offset:49152
	ds_read_b128 v[178:181], v143 offset:57344
	v_add_f32_e32 v135, v245, v135
	v_add_f32_e32 v135, v246, v135
	v_add_f32_e32 v135, v247, v135
	v_add_f32_e32 v135, v248, v135
	s_waitcnt lgkmcnt(2)
	v_mfma_f32_32x32x16_bf16 v[64:79], v[68:71], v[110:113], 0
	v_add_f32_e32 v135, v249, v135
	v_add_f32_e32 v135, v250, v135
	v_add_f32_e32 v135, v251, v135
	v_exp_f32_e32 v128, v128
	v_add_f32_e32 v135, v206, v135
	v_exp_f32_e32 v129, v129
	v_add_f32_e32 v135, v207, v135
	s_waitcnt lgkmcnt(1)
	v_mfma_f32_32x32x16_bf16 v[80:95], v[136:139], v[106:109], v[80:95]
	v_exp_f32_e32 v126, v126
	v_add_f32_e32 v135, v208, v135
	v_exp_f32_e32 v127, v127
	v_add_f32_e32 v135, v209, v135
	v_exp_f32_e32 v122, v122
	v_add_f32_e32 v135, v128, v135
	v_exp_f32_e32 v123, v123
	s_waitcnt lgkmcnt(0)
	v_mfma_f32_32x32x16_bf16 v[64:79], v[178:181], v[106:109], v[64:79]
	ds_read_b128 v[136:139], v142 offset:49152
	ds_read_b128 v[178:181], v142 offset:57344
	v_add_f32_e32 v135, v129, v135
	v_exp_f32_e32 v118, v118
	v_add_f32_e32 v135, v126, v135
	v_exp_f32_e32 v119, v119
	v_add_f32_e32 v135, v127, v135
	v_exp_f32_e32 v116, v116
	s_waitcnt lgkmcnt(1)
	v_mfma_f32_32x32x16_bf16 v[80:95], v[136:139], v[102:105], v[80:95]
	v_add_f32_e32 v135, v122, v135
	v_exp_f32_e32 v117, v117
	v_add_f32_e32 v135, v123, v135
	v_exp_f32_e32 v124, v124
	v_add_f32_e32 v135, v118, v135
	v_exp_f32_e32 v125, v125
	v_add_f32_e32 v135, v119, v135
	s_waitcnt lgkmcnt(0)
	v_mfma_f32_32x32x16_bf16 v[64:79], v[178:181], v[102:105], v[64:79]
	ds_read_b128 v[136:139], v141 offset:49152
	ds_read_b128 v[178:181], v141 offset:57344
	v_exp_f32_e32 v120, v120
	v_add_f32_e32 v135, v116, v135
	v_exp_f32_e32 v121, v121
	v_add_f32_e32 v135, v117, v135
	v_exp_f32_e32 v114, v114
	v_add_f32_e32 v135, v124, v135
	s_waitcnt lgkmcnt(1)
	v_mfma_f32_32x32x16_bf16 v[80:95], v[136:139], v[98:101], v[80:95]
	v_exp_f32_e32 v115, v115
	v_add_f32_e32 v135, v125, v135
	v_add_f32_e32 v135, v120, v135
	v_add_f32_e32 v135, v121, v135
	v_add_f32_e32 v135, v114, v135
	v_add_f32_e32 v135, v115, v135
	v_mov_b32_e32 v136, v135
	s_waitcnt lgkmcnt(0)
	v_mfma_f32_32x32x16_bf16 v[64:79], v[178:181], v[98:101], v[64:79]
	v_permlane32_swap_b32_e32 v135, v136
	v_cvt_pk_bf16_f32 v178, v240, v241
	v_cvt_pk_bf16_f32 v179, v242, v243
	v_cvt_pk_bf16_f32 v180, v244, v245
	v_cvt_pk_bf16_f32 v181, v246, v247
	v_cvt_pk_bf16_f32 v144, v248, v249
	v_cvt_pk_bf16_f32 v145, v250, v251
	v_cvt_pk_bf16_f32 v146, v206, v207
	v_cvt_pk_bf16_f32 v147, v208, v209
	v_cvt_pk_bf16_f32 v166, v128, v129
	v_cvt_pk_bf16_f32 v167, v126, v127
	v_cvt_pk_bf16_f32 v168, v122, v123
	v_cvt_pk_bf16_f32 v169, v118, v119
	v_cvt_pk_bf16_f32 v170, v116, v117
	v_cvt_pk_bf16_f32 v171, v124, v125
	v_cvt_pk_bf16_f32 v172, v120, v121
	v_cvt_pk_bf16_f32 v173, v114, v115
	s_nop 0
	v_permlane32_swap_b32_e32 v178, v180
	v_permlane32_swap_b32_e32 v179, v181
	v_permlane32_swap_b32_e32 v144, v146
	v_permlane32_swap_b32_e32 v145, v147
	v_permlane32_swap_b32_e32 v166, v168
	v_permlane32_swap_b32_e32 v167, v169
	v_permlane32_swap_b32_e32 v170, v172
	v_permlane32_swap_b32_e32 v171, v173
	v_add_u32_e32 v122, 0x10000, v96
	global_load_dwordx4 v[240:243], v96, s[58:59]
	global_load_dwordx4 v[244:247], v96, s[28:29]
	global_load_dwordx4 v[206:209], v122, s[58:59]
	s_nop 0
	global_load_dwordx4 v[248:251], v122, s[28:29]
	ds_read_b64_tr_b16 v[174:175], v160 offset:0
	ds_read_b64_tr_b16 v[176:177], v160 offset:0x800
	ds_read_b64_tr_b16 v[182:183], v160 offset:0x1000
	ds_read_b64_tr_b16 v[184:185], v160 offset:0x1800
	ds_read_b64_tr_b16 v[186:187], v160 offset:0x2000
	ds_read_b64_tr_b16 v[188:189], v160 offset:0x2800
	ds_read_b64_tr_b16 v[212:213], v160 offset:0x3000
	ds_read_b64_tr_b16 v[214:215], v160 offset:0x3800
	s_waitcnt lgkmcnt(0)
	v_mfma_f32_32x32x16_bf16 v[48:63], v[178:181], v[174:177], v[48:63]
	ds_read_b64_tr_b16 v[174:175], v160 offset:0x200
	ds_read_b64_tr_b16 v[176:177], v160 offset:0xa00
	v_max_f32_e32 v137, v81, v81
	v_max_f32_e32 v138, v80, v80
	v_max_f32_e32 v137, v138, v137
	v_max3_f32 v137, v137, v82, v83
	v_max3_f32 v137, v137, v84, v85
	v_mfma_f32_32x32x16_bf16 v[48:63], v[144:147], v[182:185], v[48:63]
	ds_read_b64_tr_b16 v[182:183], v160 offset:0x1200
	ds_read_b64_tr_b16 v[184:185], v160 offset:0x1a00
	v_max3_f32 v137, v137, v86, v87
	v_max3_f32 v137, v137, v88, v89
	v_max3_f32 v137, v137, v90, v91
	v_max3_f32 v137, v137, v92, v93
	v_max3_f32 v137, v137, v94, v95
	v_mfma_f32_32x32x16_bf16 v[48:63], v[166:169], v[186:189], v[48:63]
	ds_read_b64_tr_b16 v[186:187], v160 offset:0x2200
	ds_read_b64_tr_b16 v[188:189], v160 offset:0x2a00
	v_max3_f32 v137, v137, v64, v65
	v_max3_f32 v137, v137, v66, v67
	v_max3_f32 v137, v137, v68, v69
	v_max3_f32 v137, v137, v70, v71
	v_max3_f32 v137, v137, v72, v73
	v_mfma_f32_32x32x16_bf16 v[48:63], v[170:173], v[212:215], v[48:63]
	ds_read_b64_tr_b16 v[212:213], v160 offset:0x3200
	ds_read_b64_tr_b16 v[214:215], v160 offset:0x3a00
	v_max3_f32 v137, v137, v74, v75
	v_max3_f32 v137, v137, v76, v77
	v_max3_f32 v137, v137, v78, v79
	v_mov_b32_e32 v138, v137
	s_nop 1
	v_permlane32_swap_b32_e32 v137, v138
	s_waitcnt lgkmcnt(0)
; __device__ __forceinline__ void partialSM(f32x16& p0, f32x16& p1, float& m_reg, float& mn, float& alpha) {
;     ...
;     { auto rr = __builtin_amdgcn_permlane32_swap(__float_as_uint(pmax), __float_as_uint(pmax), false, false);
;       pmax = fmaxf(__uint_as_float(rr[0]), __uint_as_float(rr[1])); }
;     if (__builtin_expect(__all(pmax - m_reg <= THR / SCALE), 1)) { mn = m_reg; alpha = 1.f; }
;     else { mn = fmaxf(m_reg, pmax); alpha = __builtin_amdgcn_exp2f((m_reg - mn) * C); m_reg = mn; }
;     const float mnC = -mn * C;
; #pragma unroll
;     for (int r = 0; r < 16; ++r) p0[r] = fmaf(p0[r], C, mnC);
; #pragma unroll
;     for (int r = 0; r < 16; ++r) p1[r] = fmaf(p1[r], C, mnC);
; #pragma unroll
;     for (int r = 0; r < 16; ++r) p0[r] = __builtin_amdgcn_exp2f(p0[r]);
; }
	v_mfma_f32_32x32x16_bf16 v[32:47], v[178:181], v[174:177], v[32:47]
	ds_read_b64_tr_b16 v[174:175], v160 offset:0x400
	ds_read_b64_tr_b16 v[176:177], v160 offset:0xc00
	v_max_f32_e32 v138, v138, v138
	v_max_f32_e32 v137, v137, v137
	v_max_f32_e32 v137, v137, v138
	v_sub_f32_e32 v138, v137, v134
	v_cmp_ge_f32_e32 vcc, s65, v138
	v_mfma_f32_32x32x16_bf16 v[32:47], v[144:147], v[182:185], v[32:47]
	ds_read_b64_tr_b16 v[182:183], v160 offset:0x1400
	ds_read_b64_tr_b16 v[184:185], v160 offset:0x1c00
	v_max_f32_e32 v138, v134, v134
	v_max_f32_e32 v137, v138, v137
	v_sub_f32_e32 v138, v134, v137
	v_mul_f32_e32 v138, 0x3e38aa3b, v138
	v_exp_f32_e32 v138, v138
	v_mfma_f32_32x32x16_bf16 v[32:47], v[166:169], v[186:189], v[32:47]
	ds_read_b64_tr_b16 v[186:187], v160 offset:0x2400
	ds_read_b64_tr_b16 v[188:189], v160 offset:0x2c00
	s_cmp_eq_u64 vcc, exec
	s_cselect_b64 s[8:9], -1, 0
	v_cndmask_b32_e64 v138, v138, 1.0, s[8:9]
	v_cndmask_b32_e64 v134, v137, v134, s[8:9]
	v_mul_f32_e32 v137, 0xbe38aa3b, v134
	v_mfma_f32_32x32x16_bf16 v[32:47], v[170:173], v[212:215], v[32:47]
	ds_read_b64_tr_b16 v[212:213], v160 offset:0x3400
	ds_read_b64_tr_b16 v[214:215], v160 offset:0x3c00
	v_pk_fma_f32 v[80:81], v[80:81], s[72:73], v[136:137] op_sel:[0,0,1] op_sel_hi:[1,0,1]
	v_pk_fma_f32 v[82:83], v[82:83], s[72:73], v[136:137] op_sel:[0,0,1] op_sel_hi:[1,0,1]
	v_pk_fma_f32 v[84:85], v[84:85], s[72:73], v[136:137] op_sel:[0,0,1] op_sel_hi:[1,0,1]
	v_pk_fma_f32 v[86:87], v[86:87], s[72:73], v[136:137] op_sel:[0,0,1] op_sel_hi:[1,0,1]
	v_pk_fma_f32 v[88:89], v[88:89], s[72:73], v[136:137] op_sel:[0,0,1] op_sel_hi:[1,0,1]
	s_waitcnt lgkmcnt(0)
	v_mfma_f32_32x32x16_bf16 v[16:31], v[178:181], v[174:177], v[16:31]
	ds_read_b64_tr_b16 v[174:175], v160 offset:0x600
	ds_read_b64_tr_b16 v[176:177], v160 offset:0xe00
	v_pk_fma_f32 v[90:91], v[90:91], s[72:73], v[136:137] op_sel:[0,0,1] op_sel_hi:[1,0,1]
	v_pk_fma_f32 v[92:93], v[92:93], s[72:73], v[136:137] op_sel:[0,0,1] op_sel_hi:[1,0,1]
	v_pk_fma_f32 v[94:95], v[94:95], s[72:73], v[136:137] op_sel:[0,0,1] op_sel_hi:[1,0,1]
	v_exp_f32_e32 v127, v80
	v_mfma_f32_32x32x16_bf16 v[16:31], v[144:147], v[182:185], v[16:31]
	ds_read_b64_tr_b16 v[182:183], v160 offset:0x1600
	ds_read_b64_tr_b16 v[184:185], v160 offset:0x1e00
	v_exp_f32_e32 v129, v81
	v_exp_f32_e32 v125, v82
	v_exp_f32_e32 v128, v83
	v_mfma_f32_32x32x16_bf16 v[16:31], v[166:169], v[186:189], v[16:31]
	ds_read_b64_tr_b16 v[186:187], v160 offset:0x2600
	ds_read_b64_tr_b16 v[188:189], v160 offset:0x2e00
	v_exp_f32_e32 v123, v84
	v_exp_f32_e32 v126, v85
	v_exp_f32_e32 v122, v86
	v_mfma_f32_32x32x16_bf16 v[16:31], v[170:173], v[212:215], v[16:31]
	ds_read_b64_tr_b16 v[212:213], v160 offset:0x3600
	ds_read_b64_tr_b16 v[214:215], v160 offset:0x3e00
	v_exp_f32_e32 v124, v87
	v_exp_f32_e32 v119, v88
	v_exp_f32_e32 v121, v89
	s_waitcnt lgkmcnt(0)
	v_mfma_f32_32x32x16_bf16 v[0:15], v[178:181], v[174:177], v[0:15]
	s_barrier
	s_waitcnt vmcnt(0)
	ds_write_b128 v163, v[240:243]
	ds_write_b128 v164, v[206:209]
	ds_write_b128 v161, v[244:247] offset:32768
	ds_write_b128 v162, v[248:251] offset:32768
	v_exp_f32_e32 v117, v90
	v_exp_f32_e32 v120, v91
	v_exp_f32_e32 v115, v92
	v_mfma_f32_32x32x16_bf16 v[0:15], v[144:147], v[182:185], v[0:15]
	v_exp_f32_e32 v118, v93
	v_exp_f32_e32 v114, v94
	v_exp_f32_e32 v116, v95
	v_mfma_f32_32x32x16_bf16 v[0:15], v[166:169], v[186:189], v[0:15]
	v_mfma_f32_32x32x16_bf16 v[0:15], v[170:173], v[212:215], v[0:15]
	s_cmp_lg_u64 s[8:9], 0
	s_cbranch_scc1 .LBB0_284
	s_and_saveexec_b64 s[2:3], s[6:7]
	ds_write_b32 v157, v138 offset:128
	s_or_b64 exec, exec, s[2:3]
	s_waitcnt lgkmcnt(0)
	ds_read_b128 v[240:243], v158 offset:224
	ds_read_b128 v[244:247], v158 offset:192
	ds_read_b128 v[248:251], v158 offset:160
	ds_read_b128 v[206:209], v158 offset:128
	s_waitcnt lgkmcnt(3)
	v_pk_mul_f32 v[62:63], v[62:63], v[242:243]
	s_waitcnt lgkmcnt(2)
	v_pk_mul_f32 v[58:59], v[58:59], v[246:247]
	s_waitcnt lgkmcnt(1)
	v_pk_mul_f32 v[54:55], v[54:55], v[250:251]
	s_waitcnt lgkmcnt(0)
	v_pk_mul_f32 v[50:51], v[50:51], v[208:209]
	v_pk_mul_f32 v[60:61], v[60:61], v[240:241]
	v_pk_mul_f32 v[56:57], v[56:57], v[244:245]
	v_pk_mul_f32 v[52:53], v[52:53], v[248:249]
	v_pk_mul_f32 v[48:49], v[48:49], v[206:207]
	v_pk_mul_f32 v[46:47], v[46:47], v[242:243]
	v_pk_mul_f32 v[42:43], v[42:43], v[246:247]
	v_pk_mul_f32 v[38:39], v[38:39], v[250:251]
	v_pk_mul_f32 v[34:35], v[34:35], v[208:209]
	v_pk_mul_f32 v[44:45], v[44:45], v[240:241]
	v_pk_mul_f32 v[40:41], v[40:41], v[244:245]
	v_pk_mul_f32 v[36:37], v[36:37], v[248:249]
	v_pk_mul_f32 v[32:33], v[32:33], v[206:207]
	v_pk_mul_f32 v[30:31], v[30:31], v[242:243]
	v_pk_mul_f32 v[26:27], v[26:27], v[246:247]
	v_pk_mul_f32 v[22:23], v[22:23], v[250:251]
	v_pk_mul_f32 v[18:19], v[18:19], v[208:209]
	v_pk_mul_f32 v[28:29], v[28:29], v[240:241]
	v_pk_mul_f32 v[24:25], v[24:25], v[244:245]
	v_pk_mul_f32 v[20:21], v[20:21], v[248:249]
	v_pk_mul_f32 v[16:17], v[16:17], v[206:207]
	v_pk_mul_f32 v[14:15], v[14:15], v[242:243]
	v_pk_mul_f32 v[10:11], v[10:11], v[246:247]
	v_pk_mul_f32 v[6:7], v[6:7], v[250:251]
	v_pk_mul_f32 v[2:3], v[2:3], v[208:209]
	v_pk_mul_f32 v[12:13], v[12:13], v[240:241]
	v_pk_mul_f32 v[8:9], v[8:9], v[244:245]
	v_pk_mul_f32 v[4:5], v[4:5], v[248:249]
	v_pk_mul_f32 v[0:1], v[0:1], v[206:207]
; __device__ __forceinline__ void partialSM(f32x16& p0, f32x16& p1, float& m_reg, float& mn, float& alpha) {
;     constexpr float C = SCALE * 1.4426950408889634f;
;     float pmax = p0[0];
; #pragma unroll
;     for (int r = 1; r < 16; ++r) pmax = fmaxf(pmax, p0[r]);
; #pragma unroll
;     for (int r = 0; r < 16; ++r) pmax = fmaxf(pmax, p1[r]);
;     { auto rr = __builtin_amdgcn_permlane32_swap(__float_as_uint(pmax), __float_as_uint(pmax), false, false);
;       pmax = fmaxf(__uint_as_float(rr[0]), __uint_as_float(rr[1])); }
;     if (__builtin_expect(__all(pmax - m_reg <= THR / SCALE), 1)) { mn = m_reg; alpha = 1.f; }
;     else { mn = fmaxf(m_reg, pmax); alpha = __builtin_amdgcn_exp2f((m_reg - mn) * C); m_reg = mn; }
;     const float mnC = -mn * C;
; #pragma unroll
;     for (int r = 0; r < 16; ++r) p0[r] = fmaf(p0[r], C, mnC);
; #pragma unroll
;     for (int r = 0; r < 16; ++r) p1[r] = fmaf(p1[r], C, mnC);
; #pragma unroll
;     for (int r = 0; r < 16; ++r) p0[r] = __builtin_amdgcn_exp2f(p0[r]);
; }
; __device__ __forceinline__ void finishSM(f32x16& p0, f32x16& p1, float alpha, float& l_reg, bf16x8& pa0, bf16x8& pa1, bf16x8& pa2, bf16x8& pa3) {
; #pragma unroll
;     for (int r = 0; r < 16; ++r) p1[r] = __builtin_amdgcn_exp2f(p1[r]);
;     float ps = 0;
; #pragma unroll
;     for (int r = 0; r < 16; ++r) ps += p0[r];
; #pragma unroll
;     for (int r = 0; r < 16; ++r) ps += p1[r];
;     { auto rr = __builtin_amdgcn_permlane32_swap(__float_as_uint(ps), __float_as_uint(ps), false, false);
;       ps = __uint_as_float(rr[0]) + __uint_as_float(rr[1]); }
;     l_reg = l_reg * alpha + ps;
;     ...
;     PK4(p0, 0, pa0); PK4(p0, 8, pa1); PK4(p1, 0, pa2); PK4(p1, 8, pa3);
;     ...
; }
; __device__ __forceinline__ void qkt(f32x16& p0, f32x16& p1, const char* Ks, const bf16x8* qr, int r32, int hi, int comp) {
;     p0 = f32x16{}; p1 = f32x16{};
; #pragma unroll
;     for (int d0 = 0; d0 < 4; ++d0) { const int cb = (comp * 64 + d0 * 16 + hi * 8) * 2;
;         const bf16x8 b0 = *reinterpret_cast<const bf16x8*>(Ks + KSWZ(r32, cb));
;         const bf16x8 b1 = *reinterpret_cast<const bf16x8*>(Ks + KSWZ(32 + r32, cb));
;         p0 = __builtin_amdgcn_mfma_f32_32x32x16_bf16(b0, qr[d0], p0, 0, 0, 0);
;         p1 = __builtin_amdgcn_mfma_f32_32x32x16_bf16(b1, qr[d0], p1, 0, 0, 0); }
; }
.LBB0_284:
	v_fmamk_f32 v167, v64, 0x3e38aa3b, v137
	v_fmamk_f32 v168, v65, 0x3e38aa3b, v137
	v_fmamk_f32 v169, v66, 0x3e38aa3b, v137
	v_fmamk_f32 v170, v67, 0x3e38aa3b, v137
	v_fmamk_f32 v171, v68, 0x3e38aa3b, v137
	v_fmamk_f32 v144, v69, 0x3e38aa3b, v137
	v_fmamk_f32 v145, v70, 0x3e38aa3b, v137
	v_fmamk_f32 v146, v71, 0x3e38aa3b, v137
	v_fmamk_f32 v147, v72, 0x3e38aa3b, v137
	v_fmamk_f32 v148, v73, 0x3e38aa3b, v137
	v_fmamk_f32 v149, v74, 0x3e38aa3b, v137
	v_fmamk_f32 v166, v75, 0x3e38aa3b, v137
	v_fmamk_f32 v139, v76, 0x3e38aa3b, v137
	v_fmamk_f32 v172, v77, 0x3e38aa3b, v137
	v_fmamk_f32 v173, v78, 0x3e38aa3b, v137
	v_fmac_f32_e32 v137, 0x3e38aa3b, v79
	s_waitcnt lgkmcnt(0)
	s_barrier
	ds_read_b128 v[64:67], v140 offset:32768
	ds_read_b128 v[68:71], v140 offset:40960
	ds_read_b128 v[174:177], v143 offset:32768
	ds_read_b128 v[178:181], v143 offset:40960
	v_exp_f32_e32 v185, v139
	v_add_f32_e32 v139, 0, v127
	s_waitcnt lgkmcnt(3)
	v_mfma_f32_32x32x16_bf16 v[80:95], v[64:67], v[110:113], 0
	v_add_f32_e32 v139, v129, v139
	v_add_f32_e32 v139, v125, v139
	v_add_f32_e32 v139, v128, v139
	v_add_f32_e32 v139, v123, v139
	v_add_f32_e32 v139, v126, v139
	v_add_f32_e32 v139, v122, v139
	v_add_f32_e32 v139, v124, v139
	s_waitcnt lgkmcnt(2)
	v_mfma_f32_32x32x16_bf16 v[64:79], v[68:71], v[110:113], 0
	v_add_f32_e32 v139, v119, v139
	v_add_f32_e32 v139, v121, v139
	v_add_f32_e32 v139, v117, v139
	v_add_f32_e32 v139, v120, v139
	v_add_f32_e32 v139, v115, v139
	v_add_f32_e32 v139, v118, v139
	v_add_f32_e32 v139, v114, v139
	s_waitcnt lgkmcnt(1)
	v_mfma_f32_32x32x16_bf16 v[80:95], v[174:177], v[106:109], v[80:95]
	v_add_f32_e32 v139, v116, v139
	v_exp_f32_e32 v145, v145
	v_exp_f32_e32 v182, v148
	v_exp_f32_e32 v183, v149
	v_exp_f32_e32 v184, v166
	v_exp_f32_e32 v186, v172
	v_exp_f32_e32 v187, v173
	s_waitcnt lgkmcnt(0)
	v_mfma_f32_32x32x16_bf16 v[64:79], v[178:181], v[106:109], v[64:79]
	ds_read_b128 v[174:177], v142 offset:32768
	ds_read_b128 v[178:181], v142 offset:40960
	v_exp_f32_e32 v137, v137
	s_waitcnt lgkmcnt(1)
	v_mfma_f32_32x32x16_bf16 v[80:95], v[174:177], v[102:105], v[80:95]
	s_waitcnt lgkmcnt(0)
	v_mfma_f32_32x32x16_bf16 v[64:79], v[178:181], v[102:105], v[64:79]
	ds_read_b128 v[174:177], v141 offset:32768
	ds_read_b128 v[178:181], v141 offset:40960
	s_waitcnt lgkmcnt(1)
	v_mfma_f32_32x32x16_bf16 v[80:95], v[174:177], v[98:101], v[80:95]
	v_exp_f32_e32 v174, v167
	v_exp_f32_e32 v175, v168
	v_exp_f32_e32 v176, v169
	v_exp_f32_e32 v177, v170
	v_add_f32_e32 v139, v174, v139
	v_add_f32_e32 v139, v175, v139
	v_add_f32_e32 v139, v176, v139
	s_waitcnt lgkmcnt(0)
	v_mfma_f32_32x32x16_bf16 v[64:79], v[178:181], v[98:101], v[64:79]
	v_exp_f32_e32 v178, v171
	v_exp_f32_e32 v179, v144
	v_exp_f32_e32 v180, v146
	v_add_f32_e32 v139, v177, v139
	v_exp_f32_e32 v181, v147
	v_add_f32_e32 v139, v178, v139
	v_add_f32_e32 v139, v179, v139
	v_add_f32_e32 v139, v145, v139
	v_add_f32_e32 v139, v180, v139
	v_add_f32_e32 v139, v181, v139
	v_add_f32_e32 v139, v182, v139
	v_add_f32_e32 v139, v183, v139
	v_add_f32_e32 v139, v184, v139
	v_add_f32_e32 v139, v185, v139
	v_add_f32_e32 v139, v186, v139
	v_add_f32_e32 v139, v187, v139
	v_add_f32_e32 v139, v137, v139
	v_mov_b32_e32 v144, v139
	s_nop 1
	v_permlane32_swap_b32_e32 v139, v144
	v_cvt_pk_bf16_f32 v146, v127, v129
	v_cvt_pk_bf16_f32 v147, v125, v128
	v_cvt_pk_bf16_f32 v148, v123, v126
	v_cvt_pk_bf16_f32 v149, v122, v124
	v_cvt_pk_bf16_f32 v166, v119, v121
	v_cvt_pk_bf16_f32 v167, v117, v120
	v_cvt_pk_bf16_f32 v168, v115, v118
	v_cvt_pk_bf16_f32 v169, v114, v116
	v_cvt_pk_bf16_f32 v170, v174, v175
	v_cvt_pk_bf16_f32 v171, v176, v177
	v_cvt_pk_bf16_f32 v172, v178, v179
	v_cvt_pk_bf16_f32 v173, v145, v180
	v_cvt_pk_bf16_f32 v174, v181, v182
	v_cvt_pk_bf16_f32 v175, v183, v184
	v_cvt_pk_bf16_f32 v176, v185, v186
	v_cvt_pk_bf16_f32 v177, v187, v137
	s_nop 0
	v_permlane32_swap_b32_e32 v146, v148
	v_permlane32_swap_b32_e32 v147, v149
	v_permlane32_swap_b32_e32 v166, v168
	v_permlane32_swap_b32_e32 v167, v169
	v_permlane32_swap_b32_e32 v170, v172
	v_permlane32_swap_b32_e32 v171, v173
	v_permlane32_swap_b32_e32 v174, v176
	v_permlane32_swap_b32_e32 v175, v177
	v_add_u32_e32 v118, 0x20000, v96
	v_add_u32_e32 v122, 0x30000, v96
	global_load_dwordx4 v[114:117], v118, s[58:59]
	s_nop 0
	global_load_dwordx4 v[118:121], v118, s[28:29]
	s_nop 0
	global_load_dwordx4 v[126:129], v122, s[58:59]
	s_nop 0
	global_load_dwordx4 v[122:125], v122, s[28:29]
	ds_read_b64_tr_b16 v[178:179], v159 offset:0
	ds_read_b64_tr_b16 v[180:181], v159 offset:0x800
	ds_read_b64_tr_b16 v[182:183], v159 offset:0x1000
	ds_read_b64_tr_b16 v[184:185], v159 offset:0x1800
	ds_read_b64_tr_b16 v[186:187], v159 offset:0x2000
	ds_read_b64_tr_b16 v[188:189], v159 offset:0x2800
	ds_read_b64_tr_b16 v[212:213], v159 offset:0x3000
	ds_read_b64_tr_b16 v[214:215], v159 offset:0x3800
	s_waitcnt lgkmcnt(0)
	v_mfma_f32_32x32x16_bf16 v[48:63], v[146:149], v[178:181], v[48:63]
	ds_read_b64_tr_b16 v[178:179], v159 offset:0x200
	ds_read_b64_tr_b16 v[180:181], v159 offset:0xa00
	v_max_f32_e32 v255, v81, v81
	v_max_f32_e32 v210, v80, v80
	v_max_f32_e32 v255, v210, v255
	v_max3_f32 v255, v255, v82, v83
	v_max3_f32 v255, v255, v84, v85
	v_mfma_f32_32x32x16_bf16 v[48:63], v[166:169], v[182:185], v[48:63]
	ds_read_b64_tr_b16 v[182:183], v159 offset:0x1200
	ds_read_b64_tr_b16 v[184:185], v159 offset:0x1a00
	v_max3_f32 v255, v255, v86, v87
	v_max3_f32 v255, v255, v88, v89
	v_max3_f32 v255, v255, v90, v91
	v_max3_f32 v255, v255, v92, v93
	v_max3_f32 v255, v255, v94, v95
	v_mfma_f32_32x32x16_bf16 v[48:63], v[170:173], v[186:189], v[48:63]
	ds_read_b64_tr_b16 v[186:187], v159 offset:0x2200
	ds_read_b64_tr_b16 v[188:189], v159 offset:0x2a00
	v_max3_f32 v255, v255, v64, v65
	v_max3_f32 v255, v255, v66, v67
	v_max3_f32 v255, v255, v68, v69
	v_max3_f32 v255, v255, v70, v71
	v_max3_f32 v255, v255, v72, v73
	v_mfma_f32_32x32x16_bf16 v[48:63], v[174:177], v[212:215], v[48:63]
	ds_read_b64_tr_b16 v[212:213], v159 offset:0x3200
	ds_read_b64_tr_b16 v[214:215], v159 offset:0x3a00
	v_max3_f32 v255, v255, v74, v75
	v_max3_f32 v255, v255, v76, v77
	v_max3_f32 v255, v255, v78, v79
	v_mov_b32_e32 v210, v255
	s_nop 1
	v_permlane32_swap_b32_e32 v255, v210
	s_waitcnt lgkmcnt(0)
; __device__ __forceinline__ void partialSM(f32x16& p0, f32x16& p1, float& m_reg, float& mn, float& alpha) {
;     ...
;     { auto rr = __builtin_amdgcn_permlane32_swap(__float_as_uint(pmax), __float_as_uint(pmax), false, false);
;       pmax = fmaxf(__uint_as_float(rr[0]), __uint_as_float(rr[1])); }
;     if (__builtin_expect(__all(pmax - m_reg <= THR / SCALE), 1)) { mn = m_reg; alpha = 1.f; }
;     else { mn = fmaxf(m_reg, pmax); alpha = __builtin_amdgcn_exp2f((m_reg - mn) * C); m_reg = mn; }
;     const float mnC = -mn * C;
; #pragma unroll
;     for (int r = 0; r < 16; ++r) p0[r] = fmaf(p0[r], C, mnC);
; #pragma unroll
;     for (int r = 0; r < 16; ++r) p1[r] = fmaf(p1[r], C, mnC);
; #pragma unroll
;     for (int r = 0; r < 16; ++r) p0[r] = __builtin_amdgcn_exp2f(p0[r]);
; }
; __device__ __forceinline__ void finishSM(f32x16& p0, f32x16& p1, float alpha, float& l_reg, bf16x8& pa0, bf16x8& pa1, bf16x8& pa2, bf16x8& pa3) {
; #pragma unroll
;     for (int r = 0; r < 16; ++r) p1[r] = __builtin_amdgcn_exp2f(p1[r]);
;     float ps = 0;
; #pragma unroll
;     for (int r = 0; r < 16; ++r) ps += p0[r];
; #pragma unroll
;     for (int r = 0; r < 16; ++r) ps += p1[r];
;     { auto rr = __builtin_amdgcn_permlane32_swap(__float_as_uint(ps), __float_as_uint(ps), false, false);
;       ps = __uint_as_float(rr[0]) + __uint_as_float(rr[1]); }
;     l_reg = l_reg * alpha + ps;
; __device__ __forceinline__ void attn_unit(const bf16_t* Qb, const bf16_t* Kh, const bf16_t* Vh, bf16_t* Ob, float* scr, int seq, float lam, float onemli, const float* subg, char* lds) {
;     ...
;         f32x16 pA0, pA1, pB0, pB1; float mnA, mnB, alA, alB; bf16x8 pa0, pa1, pa2, pa3;
;         constexpr int SE = 0, SO = 0;
;         __syncthreads();
;         SLOAD(SE, 0); asm volatile("s_waitcnt vmcnt(0)" ::: "memory"); SWRITE(0, SE); __syncthreads();
;         qkt(pA0, pA1, K_lds, qr, r32, hi, comp); partialSM(pA0, pA1, m_reg, mnA, alA);
;         SLOAD(SO, KVBLK);
;         SWAIT(); SWRITE(1, SO); __syncthreads();
;         for (int j = 1; j + 1 < NT; j += 2) {
;             SBAR(); qkt(pB0, pB1, K_lds + SHM_K, qr, r32, hi, comp);
;             finishSM(pA0, pA1, alA, l_reg, pa0, pa1, pa2, pa3); SBAR();
;             SLOAD(SO, (j + 1) * KVBLK); SBAR();
;             pv_d0(o, vb0, pa0, pa1, pa2, pa3); partialSM(pB0, pB1, m_reg, mnB, alB);
;             __syncthreads(); SWAIT(); SWRITE(0, SE);
	v_mfma_f32_32x32x16_bf16 v[32:47], v[146:149], v[178:181], v[32:47]
	ds_read_b64_tr_b16 v[178:179], v159 offset:0x400
	ds_read_b64_tr_b16 v[180:181], v159 offset:0xc00
	v_max_f32_e32 v210, v210, v210
	v_max_f32_e32 v255, v255, v255
	v_max_f32_e32 v255, v255, v210
	v_sub_f32_e32 v210, v255, v134
	v_cmp_ge_f32_e32 vcc, s65, v210
	v_mfma_f32_32x32x16_bf16 v[32:47], v[166:169], v[182:185], v[32:47]
	ds_read_b64_tr_b16 v[182:183], v159 offset:0x1400
	ds_read_b64_tr_b16 v[184:185], v159 offset:0x1c00
	v_max_f32_e32 v210, v134, v134
	v_max_f32_e32 v210, v210, v255
	v_sub_f32_e32 v255, v134, v210
	v_mul_f32_e32 v255, 0x3e38aa3b, v255
	v_exp_f32_e32 v255, v255
	v_mfma_f32_32x32x16_bf16 v[32:47], v[170:173], v[186:189], v[32:47]
	ds_read_b64_tr_b16 v[186:187], v159 offset:0x2400
	ds_read_b64_tr_b16 v[188:189], v159 offset:0x2c00
	s_cmp_eq_u64 vcc, exec
	s_cselect_b64 s[8:9], -1, 0
	v_cndmask_b32_e64 v255, v255, 1.0, s[8:9]
	v_cndmask_b32_e64 v134, v210, v134, s[8:9]
	v_mul_f32_e32 v210, 0xbe38aa3b, v134
	v_mfma_f32_32x32x16_bf16 v[32:47], v[174:177], v[212:215], v[32:47]
	ds_read_b64_tr_b16 v[212:213], v159 offset:0x3400
	ds_read_b64_tr_b16 v[214:215], v159 offset:0x3c00
	v_pk_fma_f32 v[80:81], v[80:81], s[72:73], v[210:211] op_sel_hi:[1,0,0]
	v_pk_fma_f32 v[82:83], v[82:83], s[72:73], v[210:211] op_sel_hi:[1,0,0]
	v_pk_fma_f32 v[84:85], v[84:85], s[72:73], v[210:211] op_sel_hi:[1,0,0]
	v_pk_fma_f32 v[86:87], v[86:87], s[72:73], v[210:211] op_sel_hi:[1,0,0]
	v_pk_fma_f32 v[88:89], v[88:89], s[72:73], v[210:211] op_sel_hi:[1,0,0]
	s_waitcnt lgkmcnt(0)
	v_mfma_f32_32x32x16_bf16 v[16:31], v[146:149], v[178:181], v[16:31]
	ds_read_b64_tr_b16 v[178:179], v159 offset:0x600
	ds_read_b64_tr_b16 v[180:181], v159 offset:0xe00
	v_pk_fma_f32 v[90:91], v[90:91], s[72:73], v[210:211] op_sel_hi:[1,0,0]
	v_pk_fma_f32 v[92:93], v[92:93], s[72:73], v[210:211] op_sel_hi:[1,0,0]
	v_pk_fma_f32 v[94:95], v[94:95], s[72:73], v[210:211] op_sel_hi:[1,0,0]
	v_exp_f32_e32 v240, v80
	v_mfma_f32_32x32x16_bf16 v[16:31], v[166:169], v[182:185], v[16:31]
	ds_read_b64_tr_b16 v[182:183], v159 offset:0x1600
	ds_read_b64_tr_b16 v[184:185], v159 offset:0x1e00
	v_exp_f32_e32 v241, v81
	v_exp_f32_e32 v242, v82
	v_exp_f32_e32 v243, v83
	v_mfma_f32_32x32x16_bf16 v[16:31], v[170:173], v[186:189], v[16:31]
	ds_read_b64_tr_b16 v[186:187], v159 offset:0x2600
	ds_read_b64_tr_b16 v[188:189], v159 offset:0x2e00
	v_exp_f32_e32 v244, v84
	v_exp_f32_e32 v245, v85
	v_exp_f32_e32 v246, v86
	v_mfma_f32_32x32x16_bf16 v[16:31], v[174:177], v[212:215], v[16:31]
	ds_read_b64_tr_b16 v[212:213], v159 offset:0x3600
	ds_read_b64_tr_b16 v[214:215], v159 offset:0x3e00
	v_exp_f32_e32 v247, v87
	v_exp_f32_e32 v248, v88
	v_exp_f32_e32 v249, v89
	s_waitcnt lgkmcnt(0)
	v_mfma_f32_32x32x16_bf16 v[0:15], v[146:149], v[178:181], v[0:15]
	s_barrier
	s_waitcnt vmcnt(0)
	ds_write_b128 v163, v[114:117] offset:16384
	ds_write_b128 v164, v[126:129] offset:16384
	ds_write_b128 v161, v[118:121] offset:49152
	ds_write_b128 v162, v[122:125] offset:49152
	v_exp_f32_e32 v250, v90
	v_exp_f32_e32 v251, v91
	v_exp_f32_e32 v206, v92
	v_mfma_f32_32x32x16_bf16 v[0:15], v[166:169], v[182:185], v[0:15]
	v_exp_f32_e32 v207, v93
	v_exp_f32_e32 v208, v94
	v_exp_f32_e32 v209, v95
	v_mfma_f32_32x32x16_bf16 v[0:15], v[170:173], v[186:189], v[0:15]
	v_mfma_f32_32x32x16_bf16 v[0:15], v[174:177], v[212:215], v[0:15]
	v_mov_b32_e32 v137, v255
	s_cmp_lg_u64 s[8:9], 0
	s_cbranch_scc1 .LBB0_288
	s_and_saveexec_b64 s[2:3], s[6:7]
	ds_write_b32 v157, v137 offset:128
	s_or_b64 exec, exec, s[2:3]
	s_waitcnt lgkmcnt(0)
	ds_read_b128 v[114:117], v158 offset:224
	ds_read_b128 v[118:121], v158 offset:192
	ds_read_b128 v[122:125], v158 offset:160
	ds_read_b128 v[126:129], v158 offset:128
	s_waitcnt lgkmcnt(3)
	v_pk_mul_f32 v[62:63], v[62:63], v[116:117]
	s_waitcnt lgkmcnt(2)
	v_pk_mul_f32 v[58:59], v[58:59], v[120:121]
	s_waitcnt lgkmcnt(1)
	v_pk_mul_f32 v[54:55], v[54:55], v[124:125]
	s_waitcnt lgkmcnt(0)
	v_pk_mul_f32 v[50:51], v[50:51], v[128:129]
	v_pk_mul_f32 v[60:61], v[60:61], v[114:115]
	v_pk_mul_f32 v[56:57], v[56:57], v[118:119]
	v_pk_mul_f32 v[52:53], v[52:53], v[122:123]
	v_pk_mul_f32 v[48:49], v[48:49], v[126:127]
	v_pk_mul_f32 v[46:47], v[46:47], v[116:117]
	v_pk_mul_f32 v[42:43], v[42:43], v[120:121]
	v_pk_mul_f32 v[38:39], v[38:39], v[124:125]
	v_pk_mul_f32 v[34:35], v[34:35], v[128:129]
	v_pk_mul_f32 v[44:45], v[44:45], v[114:115]
	v_pk_mul_f32 v[40:41], v[40:41], v[118:119]
	v_pk_mul_f32 v[36:37], v[36:37], v[122:123]
	v_pk_mul_f32 v[32:33], v[32:33], v[126:127]
	v_pk_mul_f32 v[30:31], v[30:31], v[116:117]
	v_pk_mul_f32 v[26:27], v[26:27], v[120:121]
	v_pk_mul_f32 v[22:23], v[22:23], v[124:125]
	v_pk_mul_f32 v[18:19], v[18:19], v[128:129]
	v_pk_mul_f32 v[28:29], v[28:29], v[114:115]
	v_pk_mul_f32 v[24:25], v[24:25], v[118:119]
	v_pk_mul_f32 v[20:21], v[20:21], v[122:123]
	v_pk_mul_f32 v[16:17], v[16:17], v[126:127]
	v_pk_mul_f32 v[14:15], v[14:15], v[116:117]
	v_pk_mul_f32 v[10:11], v[10:11], v[120:121]
	v_pk_mul_f32 v[6:7], v[6:7], v[124:125]
	v_pk_mul_f32 v[2:3], v[2:3], v[128:129]
	v_pk_mul_f32 v[12:13], v[12:13], v[114:115]
	v_pk_mul_f32 v[8:9], v[8:9], v[118:119]
	v_pk_mul_f32 v[4:5], v[4:5], v[122:123]
	v_pk_mul_f32 v[0:1], v[0:1], v[126:127]
.LBB0_288:
	v_mov_b32_e32 v114, v210
	v_pk_fma_f32 v[128:129], v[64:65], s[72:73], v[114:115] op_sel_hi:[1,0,0]
	v_add_f32_e32 v64, v135, v136
	v_fmac_f32_e32 v64, v133, v132
	v_add_f32_e32 v132, v139, v144
	s_add_i32 s36, s36, 2
	v_pk_fma_f32 v[126:127], v[66:67], s[72:73], v[114:115] op_sel_hi:[1,0,0]
	v_pk_fma_f32 v[122:123], v[68:69], s[72:73], v[114:115] op_sel_hi:[1,0,0]
	v_pk_fma_f32 v[118:119], v[70:71], s[72:73], v[114:115] op_sel_hi:[1,0,0]
	v_pk_fma_f32 v[116:117], v[72:73], s[72:73], v[114:115] op_sel_hi:[1,0,0]
	v_pk_fma_f32 v[124:125], v[74:75], s[72:73], v[114:115] op_sel_hi:[1,0,0]
	v_pk_fma_f32 v[120:121], v[76:77], s[72:73], v[114:115] op_sel_hi:[1,0,0]
	v_pk_fma_f32 v[114:115], v[78:79], s[72:73], v[114:115] op_sel_hi:[1,0,0]
	v_fmac_f32_e32 v132, v64, v138
	s_cmp_lt_u32 s36, s67
	v_add_u32_e32 v96, 0x40000, v96
	v_mov_b32_e32 v133, v137
	s_waitcnt lgkmcnt(0)
	s_barrier
	s_cbranch_scc1 .LBB0_280
